# phase 3: workgroups 128..255 start ~2.7 us late (s_sleep 100) to split the tile-epilogue burst
# speedup vs baseline: 1.0020x; 1.0020x over previous
.LBB0_974:
	s_cmpk_lt_u32 s92, 0x80
	s_cbranch_scc1 .Lp3d_go
	s_sleep 100
